# sel relaxed loop copy: reloaded blocks are never forced, so the slot test and LDS path are removed from its four reload sites
# baseline (speedup 1.0000x reference)
; #define LAS __attribute__((address_space(3)))
; #define SEL_IDX(i) __shfl(myidx, (i) < last ? (i) : last)
; __device__ __forceinline__ void sel_load(SelBuf& B, const unsigned char* Kb, const unsigned char* Vb, int jb, int cc, int q4) {
; #pragma unroll
;     for (int ht = 0; ht < 4; ++ht) { const int keyrow = jb * 64 + 32 * (ht >> 1) + 8 * (cc >> 2) + (cc & 3) + 4 * (ht & 1);
;         B.k[ht] = *(const l64x2*)(Kb + (size_t)keyrow * 64 + q4 * 16); }
; #pragma unroll
;     for (int d = 0; d < 4; ++d) B.v[d] = *(const l64x2*)(Vb + ((size_t)jb * 64 + 16 * d + cc) * 64 + q4 * 16);
; }
; __device__ __forceinline__ void sel_load_any(SelBuf& B, const unsigned char* Kb, const unsigned char* Vb, const LAS unsigned char* fl, int jb, int cur, int cc, int q4) {
;     const int slot = (jb == 0) ? 0 : ((jb == cur - 1) ? 1 : ((jb == cur) ? 2 : -1));
;     if (slot < 0) { sel_load(B, Kb, Vb, jb, cc, q4); return; }
; __device__ __forceinline__ void phase_sel(const Params& p, LAS unsigned char* lds, const bf16_t* Z, const float* G, const unsigned char* K8, const unsigned char* V8T, const float* ACC, const int* IDX, bf16_t* Mixed, int tid, int wid, int lane) {
;     ...
;         for (int k = 0; k < nblk; k += 4) {
;             sel_compute2(m, l, o, qf, b0, b1, j0 * 64, j1 * 64, j0 == cur, j1 == cur, k + 1 < nblk, t, c, q4);
;             if (k + 4 < nblk) { j0 = SEL_IDX(k + 4); j1 = SEL_IDX(k + 5); sel_load_any(b0, Kb, Vb, lds, j0, cur, cc, q4); sel_load_any(b1, Kb, Vb, lds, j1, cur, cc, q4); }
;             if (k + 2 < nblk) sel_compute2(m, l, o, qf, b2, b3, j2 * 64, j3 * 64, j2 == cur, j3 == cur, k + 3 < nblk, t, c, q4);
;             if (k + 6 < nblk) { j2 = SEL_IDX(k + 6); j3 = SEL_IDX(k + 7); sel_load_any(b2, Kb, Vb, lds, j2, cur, cc, q4); sel_load_any(b3, Kb, Vb, lds, j3, cur, cc, q4); }
.Lsr_716:
	v_mov_b64_e32 v[182:183], s[64:65]
	v_fma_f32 v183, -v214, s62, v182
	v_pk_fma_f32 v[170:171], v[170:171], s[62:63], v[182:183] op_sel:[0,0,1] op_sel_hi:[1,0,1]
	v_pk_fma_f32 v[166:167], v[166:167], s[62:63], v[182:183] op_sel:[0,0,1] op_sel_hi:[1,0,1]
	v_exp_f32_e32 v170, v170
	v_exp_f32_e32 v171, v171
	v_exp_f32_e32 v166, v166
	v_exp_f32_e32 v167, v167
	v_pk_fma_f32 v[172:173], v[172:173], s[62:63], v[182:183] op_sel:[0,0,1] op_sel_hi:[1,0,1]
	v_pk_fma_f32 v[168:169], v[168:169], s[62:63], v[182:183] op_sel:[0,0,1] op_sel_hi:[1,0,1]
	v_pk_fma_f32 v[162:163], v[162:163], s[62:63], v[182:183] op_sel:[0,0,1] op_sel_hi:[1,0,1]
	v_pk_fma_f32 v[164:165], v[164:165], s[62:63], v[182:183] op_sel:[0,0,1] op_sel_hi:[1,0,1]
	v_pk_fma_f32 v[174:175], v[174:175], s[62:63], v[182:183] op_sel:[0,0,1] op_sel_hi:[1,0,1]
	v_pk_fma_f32 v[176:177], v[176:177], s[62:63], v[182:183] op_sel:[0,0,1] op_sel_hi:[1,0,1]
	v_pk_fma_f32 v[150:151], v[150:151], s[62:63], v[182:183] op_sel:[0,0,1] op_sel_hi:[1,0,1]
	v_pk_fma_f32 v[152:153], v[152:153], s[62:63], v[182:183] op_sel:[0,0,1] op_sel_hi:[1,0,1]
	v_pk_fma_f32 v[146:147], v[146:147], s[62:63], v[182:183] op_sel:[0,0,1] op_sel_hi:[1,0,1]
	v_pk_fma_f32 v[148:149], v[148:149], s[62:63], v[182:183] op_sel:[0,0,1] op_sel_hi:[1,0,1]
	v_pk_fma_f32 v[154:155], v[154:155], s[62:63], v[182:183] op_sel:[0,0,1] op_sel_hi:[1,0,1]
	v_pk_fma_f32 v[156:157], v[156:157], s[62:63], v[182:183] op_sel:[0,0,1] op_sel_hi:[1,0,1]
	v_pk_fma_f32 v[158:159], v[158:159], s[62:63], v[182:183] op_sel:[0,0,1] op_sel_hi:[1,0,1]
	v_pk_fma_f32 v[160:161], v[160:161], s[62:63], v[182:183] op_sel:[0,0,1] op_sel_hi:[1,0,1]
	v_exp_f32_e32 v172, v172
	v_exp_f32_e32 v173, v173
	v_exp_f32_e32 v168, v168
	v_exp_f32_e32 v169, v169
	v_exp_f32_e32 v150, v150
	v_exp_f32_e32 v151, v151
	v_exp_f32_e32 v146, v146
	v_exp_f32_e32 v147, v147
	v_cvt_pk_fp8_f32 v182, v170, v171
	v_cvt_pk_fp8_f32 v183, v166, v167
	v_exp_f32_e32 v152, v152
	v_exp_f32_e32 v153, v153
	v_exp_f32_e32 v148, v148
	v_exp_f32_e32 v149, v149
	v_cvt_pk_fp8_f32 v182, v172, v173 op_sel:[0,0,1]
	v_cvt_pk_fp8_f32 v183, v168, v169 op_sel:[0,0,1]
	v_cvt_pk_fp8_f32 v184, v150, v151
	v_cvt_pk_fp8_f32 v185, v146, v147
	v_exp_f32_e32 v162, v162
	v_exp_f32_e32 v163, v163
	v_exp_f32_e32 v174, v174
	v_exp_f32_e32 v175, v175
	v_cvt_pk_fp8_f32 v184, v152, v153 op_sel:[0,0,1]
	v_cvt_pk_fp8_f32 v185, v148, v149 op_sel:[0,0,1]
	s_waitcnt vmcnt(19)
	v_mfma_f32_16x16x32_fp8_fp8 v[142:145], v[18:19], v[182:183], v[142:145]
	v_exp_f32_e32 v164, v164
	v_exp_f32_e32 v165, v165
	v_exp_f32_e32 v176, v176
	s_waitcnt vmcnt(18)
	v_mfma_f32_16x16x32_fp8_fp8 v[138:141], v[26:27], v[182:183], v[138:141]
	v_exp_f32_e32 v177, v177
	v_exp_f32_e32 v154, v154
	v_exp_f32_e32 v155, v155
	s_waitcnt vmcnt(17)
	v_mfma_f32_16x16x32_fp8_fp8 v[110:113], v[30:31], v[182:183], v[110:113]
	v_exp_f32_e32 v158, v158
	v_exp_f32_e32 v159, v159
	v_exp_f32_e32 v156, v156
	s_waitcnt vmcnt(16)
	v_mfma_f32_16x16x32_fp8_fp8 v[98:101], v[22:23], v[182:183], v[98:101]
	v_cvt_pk_fp8_f32 v182, v162, v163
	v_cvt_pk_fp8_f32 v183, v174, v175
	v_mfma_f32_16x16x32_fp8_fp8 v[142:145], v[66:67], v[184:185], v[142:145]
	v_exp_f32_e32 v157, v157
	v_exp_f32_e32 v160, v160
	v_exp_f32_e32 v161, v161
	v_mfma_f32_16x16x32_fp8_fp8 v[138:141], v[78:79], v[184:185], v[138:141]
	v_cvt_pk_fp8_f32 v182, v164, v165 op_sel:[0,0,1]
	v_cvt_pk_fp8_f32 v183, v176, v177 op_sel:[0,0,1]
	s_add_i32 s71, s70, 4
	v_mfma_f32_16x16x32_fp8_fp8 v[110:113], v[90:91], v[184:185], v[110:113]
	s_cmp_ge_u32 s71, s26
	s_cselect_b64 s[16:17], -1, 0
	s_and_b64 vcc, exec, s[16:17]
	v_mfma_f32_16x16x32_fp8_fp8 v[98:101], v[86:87], v[184:185], v[98:101]
	v_cvt_pk_fp8_f32 v184, v154, v155
	v_cvt_pk_fp8_f32 v185, v158, v159
	v_mfma_f32_16x16x32_fp8_fp8 v[142:145], v[20:21], v[182:183], v[142:145]
	v_cvt_pk_fp8_f32 v184, v156, v157 op_sel:[0,0,1]
	v_cvt_pk_fp8_f32 v185, v160, v161 op_sel:[0,0,1]
	v_mfma_f32_16x16x32_fp8_fp8 v[138:141], v[28:29], v[182:183], v[138:141]
	v_mfma_f32_16x16x32_fp8_fp8 v[110:113], v[32:33], v[182:183], v[110:113]
	v_mfma_f32_16x16x32_fp8_fp8 v[98:101], v[24:25], v[182:183], v[98:101]
	v_mfma_f32_16x16x32_fp8_fp8 v[142:145], v[68:69], v[184:185], v[142:145]
	v_mfma_f32_16x16x32_fp8_fp8 v[138:141], v[80:81], v[184:185], v[138:141]
	v_mfma_f32_16x16x32_fp8_fp8 v[110:113], v[92:93], v[184:185], v[110:113]
	v_mfma_f32_16x16x32_fp8_fp8 v[98:101], v[88:89], v[184:185], v[98:101]
	s_waitcnt vmcnt(0)
	s_cbranch_vccnz .Lsr_726
	v_and_or_b32 v2, s71, 60, v181
	v_lshlrev_b32_e32 v2, 2, v2
	ds_bpermute_b32 v198, v2, v246
	s_add_i32 s2, s70, 5
	s_min_i32 s2, s2, s69
	v_and_or_b32 v2, s2, 63, v181
	v_lshlrev_b32_e32 v2, 2, v2
	ds_bpermute_b32 v202, v2, v246
	s_waitcnt lgkmcnt(1)
	s_waitcnt lgkmcnt(5)
	v_ashrrev_i32_e32 v199, 31, v198
	s_waitcnt lgkmcnt(3)
	v_lshlrev_b64 v[18:19], 12, v[198:199]
	s_waitcnt lgkmcnt(0)
	v_lshl_add_u64 v[22:23], v[212:213], 0, v[18:19]
	v_lshl_or_b32 v14, v198, 6, v193
	v_ashrrev_i32_e32 v15, 31, v14
	v_lshlrev_b64 v[14:15], 6, v[14:15]
	v_lshl_add_u64 v[14:15], v[206:207], 0, v[14:15]
	global_load_dwordx4 v[2:5], v[14:15], off
	global_load_dwordx4 v[6:9], v[14:15], off offset:256
	global_load_dwordx4 v[10:13], v[14:15], off offset:2048
	s_nop 0
	global_load_dwordx4 v[14:17], v[14:15], off offset:2304
	s_nop 0
	global_load_dwordx4 v[18:21], v[22:23], off
	global_load_dwordx4 v[26:29], v[22:23], off offset:1024
	global_load_dwordx4 v[30:33], v[22:23], off offset:2048
	s_nop 0
	global_load_dwordx4 v[22:25], v[22:23], off offset:3072
	s_waitcnt lgkmcnt(0)
	s_waitcnt lgkmcnt(5)
	v_ashrrev_i32_e32 v203, 31, v202
	s_waitcnt lgkmcnt(3)
	v_lshlrev_b64 v[66:67], 12, v[202:203]
	s_waitcnt lgkmcnt(0)
	v_lshl_add_u64 v[86:87], v[212:213], 0, v[66:67]
	v_lshl_or_b32 v58, v202, 6, v193
	v_ashrrev_i32_e32 v59, 31, v58
	v_lshlrev_b64 v[58:59], 6, v[58:59]
	v_lshl_add_u64 v[58:59], v[206:207], 0, v[58:59]
	global_load_dwordx4 v[34:37], v[58:59], off
	global_load_dwordx4 v[42:45], v[58:59], off offset:256
	global_load_dwordx4 v[50:53], v[58:59], off offset:2048
	s_nop 0
	global_load_dwordx4 v[58:61], v[58:59], off offset:2304
	s_nop 0
	global_load_dwordx4 v[66:69], v[86:87], off
	global_load_dwordx4 v[78:81], v[86:87], off offset:1024
	global_load_dwordx4 v[90:93], v[86:87], off offset:2048
	s_nop 0
	global_load_dwordx4 v[86:89], v[86:87], off offset:3072

; #define LAS __attribute__((address_space(3)))
; #define SEL_IDX(i) __shfl(myidx, (i) < last ? (i) : last)
; __device__ __forceinline__ void sel_load(SelBuf& B, const unsigned char* Kb, const unsigned char* Vb, int jb, int cc, int q4) {
; #pragma unroll
;     for (int ht = 0; ht < 4; ++ht) { const int keyrow = jb * 64 + 32 * (ht >> 1) + 8 * (cc >> 2) + (cc & 3) + 4 * (ht & 1);
;         B.k[ht] = *(const l64x2*)(Kb + (size_t)keyrow * 64 + q4 * 16); }
; #pragma unroll
;     for (int d = 0; d < 4; ++d) B.v[d] = *(const l64x2*)(Vb + ((size_t)jb * 64 + 16 * d + cc) * 64 + q4 * 16);
; }
; __device__ __forceinline__ void sel_load_any(SelBuf& B, const unsigned char* Kb, const unsigned char* Vb, const LAS unsigned char* fl, int jb, int cur, int cc, int q4) {
;     const int slot = (jb == 0) ? 0 : ((jb == cur - 1) ? 1 : ((jb == cur) ? 2 : -1));
;     if (slot < 0) { sel_load(B, Kb, Vb, jb, cc, q4); return; }
; __device__ __forceinline__ void phase_sel(const Params& p, LAS unsigned char* lds, const bf16_t* Z, const float* G, const unsigned char* K8, const unsigned char* V8T, const float* ACC, const int* IDX, bf16_t* Mixed, int tid, int wid, int lane) {
;     ...
;             if (k + 4 < nblk) { j0 = SEL_IDX(k + 4); j1 = SEL_IDX(k + 5); sel_load_any(b0, Kb, Vb, lds, j0, cur, cc, q4); sel_load_any(b1, Kb, Vb, lds, j1, cur, cc, q4); }
;             if (k + 2 < nblk) sel_compute2(m, l, o, qf, b2, b3, j2 * 64, j3 * 64, j2 == cur, j3 == cur, k + 3 < nblk, t, c, q4);
;             if (k + 6 < nblk) { j2 = SEL_IDX(k + 6); j3 = SEL_IDX(k + 7); sel_load_any(b2, Kb, Vb, lds, j2, cur, cc, q4); sel_load_any(b3, Kb, Vb, lds, j3, cur, cc, q4); }
.Lsr_798:
	v_and_or_b32 v38, s2, 62, v181
	v_lshlrev_b32_e32 v38, 2, v38
	ds_bpermute_b32 v200, v38, v246
	s_add_i32 s2, s70, 7
	s_min_i32 s2, s2, s69
	v_and_or_b32 v38, s2, 63, v181
	v_lshlrev_b32_e32 v38, 2, v38
	ds_bpermute_b32 v204, v38, v246
	s_waitcnt lgkmcnt(1)
	s_waitcnt lgkmcnt(5)
	v_ashrrev_i32_e32 v201, 31, v200
	s_waitcnt lgkmcnt(3)
	v_lshlrev_b64 v[70:71], 12, v[200:201]
	s_waitcnt lgkmcnt(0)
	v_lshl_add_u64 v[74:75], v[212:213], 0, v[70:71]
	v_lshl_or_b32 v62, v200, 6, v193
	v_ashrrev_i32_e32 v63, 31, v62
	v_lshlrev_b64 v[62:63], 6, v[62:63]
	v_lshl_add_u64 v[62:63], v[206:207], 0, v[62:63]
	global_load_dwordx4 v[38:41], v[62:63], off
	global_load_dwordx4 v[46:49], v[62:63], off offset:256
	global_load_dwordx4 v[54:57], v[62:63], off offset:2048
	s_nop 0
	global_load_dwordx4 v[62:65], v[62:63], off offset:2304
	s_nop 0
	global_load_dwordx4 v[70:73], v[74:75], off
	global_load_dwordx4 v[82:85], v[74:75], off offset:1024
	global_load_dwordx4 v[94:97], v[74:75], off offset:2048
	s_nop 0
	global_load_dwordx4 v[74:77], v[74:75], off offset:3072
	s_waitcnt lgkmcnt(0)
	s_waitcnt lgkmcnt(5)
	v_ashrrev_i32_e32 v205, 31, v204
	s_waitcnt lgkmcnt(3)
	v_lshlrev_b64 v[122:123], 12, v[204:205]
	s_waitcnt lgkmcnt(0)
	v_lshl_add_u64 v[130:131], v[212:213], 0, v[122:123]
	v_lshl_or_b32 v118, v204, 6, v193
	v_ashrrev_i32_e32 v119, 31, v118
	v_lshlrev_b64 v[118:119], 6, v[118:119]
	v_lshl_add_u64 v[118:119], v[206:207], 0, v[118:119]
	global_load_dwordx4 v[102:105], v[118:119], off
	global_load_dwordx4 v[106:109], v[118:119], off offset:256
	global_load_dwordx4 v[114:117], v[118:119], off offset:2048
	s_nop 0
	global_load_dwordx4 v[118:121], v[118:119], off offset:2304
	s_nop 0
	global_load_dwordx4 v[122:125], v[130:131], off
	global_load_dwordx4 v[126:129], v[130:131], off offset:1024
	global_load_dwordx4 v[134:137], v[130:131], off offset:2048
	s_nop 0
	global_load_dwordx4 v[130:133], v[130:131], off offset:3072
